# k17 + res_pipe7/11: residual GEMM epilogues re-pipelined (all loads queued ahead of stores, counted waits per 16-row group)
# baseline (speedup 1.0000x reference)
; #define PG8_STAGE(bufoff, gbase, voff) do { _Pragma("unroll") for (int _i = 0; _i < 2; ++_i) \
;         __builtin_amdgcn_global_load_lds((const unsigned*)((const char*)(gbase) + (voff)[_i]), (LAS unsigned*)(lds + (bufoff) + ldsw + _i * 8192), 16, 0, 0); } while (0)
; #define PG8_LDA(dst, b, h) do { _Pragma("unroll") for (int m = 0; m < 4; ++m) _Pragma("unroll") for (int k = 0; k < 2; ++k) dst[m][k] = *(const LAS bf16x8*)(lds + PG8_SA(b, h) + aoff + m * 2048 + k * 1024); } while (0)
; #define PG8_LDB(dst, b, h) do { _Pragma("unroll") for (int n = 0; n < 2; ++n) _Pragma("unroll") for (int k = 0; k < 2; ++k) dst[n][k] = *(const LAS bf16x8*)(lds + PG8_SB(b, h) + boff + n * 2048 + k * 1024); } while (0)
; #define PG8_WAIT_V(n) asm volatile("s_waitcnt vmcnt(" #n ")" ::: "memory")
; #define PG8_WAIT_L(n) asm volatile("s_waitcnt lgkmcnt(" #n ")" ::: "memory")
; #define PG8_BAR __builtin_amdgcn_s_barrier()
; #define PG8_SCHED __builtin_amdgcn_sched_barrier(0)
; template <class Epi>
; __device__ __forceinline__ void gemm_phase(LAS unsigned char* lds, const Gemm g, const StaticOrder& S, const Epi& E, int wave) {
;     ...
;         for (int t = 0; t < nt; t += 2) {
;             const bool last = (t == nt - 2);
;             const char* a1 = cA + (size_t)(t + 1) * kstep;
;             const char* a2 = last ? nA : cA + (size_t)(t + 2) * kstep; const char* b2 = last ? nB : cB + (size_t)(t + 2) * kstep;
;             const char* a3 = a2 + kstep; const char* b3 = b2 + kstep;
;             PG8_LDB(B0, 0, 0); PG8_SCHED; PG8_LDA(At, 0, 0); PG8_STAGE(PG8_SA(1, 1), a1 + hstep, voffA);
;             PG8_WAIT_L(8); PG8_BAR; PG8_WAIT_L(0); PG8_MMA(0, 0, At, B0); PG8_BAR; PG8_SCHED;
;             PG8_LDB(B1, 0, 1); PG8_STAGE(PG8_SB(0, 0), b2, voffB);
;             PG8_BAR; PG8_WAIT_L(0); PG8_MMA(0, 1, At, B1); PG8_BAR;
;             PG8_LDA(At, 0, 1); PG8_STAGE(PG8_SA(0, 0), a2, voffA);
;             PG8_BAR; PG8_WAIT_L(0); PG8_MMA(1, 0, At, B0); PG8_BAR; PG8_SCHED;
;             PG8_STAGE(PG8_SB(0, 1), b2 + hstep, voffB);
;             PG8_WAIT_V(6); PG8_BAR; PG8_MMA(1, 1, At, B1); PG8_BAR;
;             PG8_LDB(B0, 1, 0); PG8_SCHED; PG8_LDA(At, 1, 0); PG8_STAGE(PG8_SA(0, 1), a2 + hstep, voffA);
;             PG8_WAIT_L(8); PG8_BAR; PG8_WAIT_L(0); PG8_MMA(0, 0, At, B0); PG8_BAR; PG8_SCHED;
.LBB0_767:
	ds_read_b128 v[128:131], v163
	ds_read_b128 v[132:135], v163 offset:1024
	ds_read_b128 v[136:139], v163 offset:2048
	ds_read_b128 v[140:143], v163 offset:3072
	s_add_u32 s28, s26, 0x100
	s_addc_u32 s29, s27, 0
	s_cmp_eq_u32 s62, 12
	s_cselect_b32 s35, s19, s29
	s_cselect_b32 s34, s58, s28
	s_cselect_b32 s31, s17, s61
	s_cselect_b32 s30, s59, s60
	v_lshl_add_u64 v[160:161], s[26:27], 0, v[148:149]
	s_add_i32 m0, s25, 0xc000
	ds_read_b128 v[156:159], v164
	ds_read_b128 v[166:169], v164 offset:1024
	ds_read_b128 v[170:173], v164 offset:2048
	ds_read_b128 v[174:177], v164 offset:3072
	ds_read_b128 v[178:181], v164 offset:4096
	ds_read_b128 v[182:185], v164 offset:5120
	ds_read_b128 v[186:189], v164 offset:6144
	ds_read_b128 v[190:193], v164 offset:7168
	global_load_lds_dwordx4 v[160:161], off
	v_lshl_add_u64 v[160:161], s[26:27], 0, v[150:151]
	s_add_i32 m0, s25, 0xe000
	s_nop 0
	global_load_lds_dwordx4 v[160:161], off
	s_waitcnt lgkmcnt(8)
	s_barrier
	s_waitcnt lgkmcnt(0)
	s_setprio 1
	s_waitcnt lgkmcnt(0)
	v_mfma_f32_16x16x32_bf16 v[124:127], v[128:131], v[156:159], v[124:127]
	v_mfma_f32_16x16x32_bf16 v[120:123], v[136:139], v[156:159], v[120:123]
	v_mfma_f32_16x16x32_bf16 v[116:119], v[128:131], v[170:173], v[116:119]
	v_mfma_f32_16x16x32_bf16 v[112:115], v[136:139], v[170:173], v[112:115]
	v_mfma_f32_16x16x32_bf16 v[108:111], v[128:131], v[178:181], v[108:111]
	v_mfma_f32_16x16x32_bf16 v[96:99], v[136:139], v[178:181], v[96:99]
	v_mfma_f32_16x16x32_bf16 v[84:87], v[128:131], v[186:189], v[84:87]
	v_mfma_f32_16x16x32_bf16 v[72:75], v[136:139], v[186:189], v[72:75]
	v_mfma_f32_16x16x32_bf16 v[124:127], v[132:135], v[166:169], v[124:127]
	v_mfma_f32_16x16x32_bf16 v[120:123], v[140:143], v[166:169], v[120:123]
	v_mfma_f32_16x16x32_bf16 v[116:119], v[132:135], v[174:177], v[116:119]
	v_mfma_f32_16x16x32_bf16 v[112:115], v[140:143], v[174:177], v[112:115]
	v_mfma_f32_16x16x32_bf16 v[108:111], v[132:135], v[182:185], v[108:111]
	v_mfma_f32_16x16x32_bf16 v[96:99], v[140:143], v[182:185], v[96:99]
	v_mfma_f32_16x16x32_bf16 v[84:87], v[132:135], v[190:193], v[84:87]
	v_mfma_f32_16x16x32_bf16 v[72:75], v[140:143], v[190:193], v[72:75]
	s_setprio 0
	s_barrier
	s_add_i32 s26, s55, s39
	v_lshl_add_u64 v[160:161], s[30:31], 0, v[146:147]
	s_mov_b32 m0, s26
	ds_read_b128 v[194:197], v165
	ds_read_b128 v[198:201], v165 offset:1024
	ds_read_b128 v[202:205], v165 offset:2048
	ds_read_b128 v[206:209], v165 offset:3072
	global_load_lds_dwordx4 v[160:161], off
	v_lshl_add_u64 v[210:211], s[30:31], 0, v[144:145]
	s_add_i32 m0, s26, 0x2000
	s_nop 0
	global_load_lds_dwordx4 v[210:211], off
	s_barrier
	s_waitcnt lgkmcnt(0)
	s_setprio 1
	s_waitcnt lgkmcnt(0)
	v_mfma_f32_16x16x32_bf16 v[104:107], v[194:197], v[156:159], v[104:107]
	v_mfma_f32_16x16x32_bf16 v[100:103], v[202:205], v[156:159], v[100:103]
	v_mfma_f32_16x16x32_bf16 v[92:95], v[194:197], v[170:173], v[92:95]
	v_mfma_f32_16x16x32_bf16 v[88:91], v[202:205], v[170:173], v[88:91]
	v_mfma_f32_16x16x32_bf16 v[80:83], v[194:197], v[178:181], v[80:83]
	v_mfma_f32_16x16x32_bf16 v[76:79], v[202:205], v[178:181], v[76:79]
	v_mfma_f32_16x16x32_bf16 v[68:71], v[194:197], v[186:189], v[68:71]
	v_mfma_f32_16x16x32_bf16 v[64:67], v[202:205], v[186:189], v[64:67]
	v_mfma_f32_16x16x32_bf16 v[104:107], v[198:201], v[166:169], v[104:107]
	v_mfma_f32_16x16x32_bf16 v[100:103], v[206:209], v[166:169], v[100:103]
	v_mfma_f32_16x16x32_bf16 v[92:95], v[198:201], v[174:177], v[92:95]
	v_mfma_f32_16x16x32_bf16 v[88:91], v[206:209], v[174:177], v[88:91]
	v_mfma_f32_16x16x32_bf16 v[80:83], v[198:201], v[182:185], v[80:83]
	v_mfma_f32_16x16x32_bf16 v[76:79], v[206:209], v[182:185], v[76:79]
	v_mfma_f32_16x16x32_bf16 v[68:71], v[198:201], v[190:193], v[68:71]
	v_mfma_f32_16x16x32_bf16 v[64:67], v[206:209], v[190:193], v[64:67]
	s_setprio 0
	s_mov_b32 m0, s25
	v_lshl_add_u64 v[212:213], s[34:35], 0, v[146:147]
	s_barrier
	ds_read_b128 v[156:159], v164 offset:16384
	ds_read_b128 v[166:169], v164 offset:17408
	ds_read_b128 v[170:173], v164 offset:18432
	ds_read_b128 v[174:177], v164 offset:19456
	ds_read_b128 v[178:181], v164 offset:20480
	ds_read_b128 v[182:185], v164 offset:21504
	ds_read_b128 v[186:189], v164 offset:22528
	ds_read_b128 v[190:193], v164 offset:23552
	global_load_lds_dwordx4 v[212:213], off
	v_lshl_add_u64 v[214:215], s[34:35], 0, v[144:145]
	s_mov_b32 m0, s42
	s_nop 0
	global_load_lds_dwordx4 v[214:215], off
	s_barrier
	s_waitcnt lgkmcnt(0)
	s_setprio 1
	s_waitcnt lgkmcnt(0)
	v_mfma_f32_16x16x32_bf16 v[60:63], v[128:131], v[156:159], v[60:63]
	v_mfma_f32_16x16x32_bf16 v[56:59], v[136:139], v[156:159], v[56:59]
	v_mfma_f32_16x16x32_bf16 v[52:55], v[128:131], v[170:173], v[52:55]
	v_mfma_f32_16x16x32_bf16 v[48:51], v[136:139], v[170:173], v[48:51]
	v_mfma_f32_16x16x32_bf16 v[44:47], v[128:131], v[178:181], v[44:47]
	v_mfma_f32_16x16x32_bf16 v[32:35], v[136:139], v[178:181], v[32:35]
	v_mfma_f32_16x16x32_bf16 v[20:23], v[128:131], v[186:189], v[20:23]
	v_mfma_f32_16x16x32_bf16 v[8:11], v[136:139], v[186:189], v[8:11]
	v_mfma_f32_16x16x32_bf16 v[60:63], v[132:135], v[166:169], v[60:63]
	v_mfma_f32_16x16x32_bf16 v[56:59], v[140:143], v[166:169], v[56:59]
	v_mfma_f32_16x16x32_bf16 v[52:55], v[132:135], v[174:177], v[52:55]
	v_mfma_f32_16x16x32_bf16 v[48:51], v[140:143], v[174:177], v[48:51]
	v_mfma_f32_16x16x32_bf16 v[44:47], v[132:135], v[182:185], v[44:47]
	v_mfma_f32_16x16x32_bf16 v[32:35], v[140:143], v[182:185], v[32:35]
	v_mfma_f32_16x16x32_bf16 v[20:23], v[132:135], v[190:193], v[20:23]
	v_mfma_f32_16x16x32_bf16 v[8:11], v[140:143], v[190:193], v[8:11]
	s_setprio 0
	s_barrier
; #define PG8_STAGE(bufoff, gbase, voff) do { _Pragma("unroll") for (int _i = 0; _i < 2; ++_i) \
;         __builtin_amdgcn_global_load_lds((const unsigned*)((const char*)(gbase) + (voff)[_i]), (LAS unsigned*)(lds + (bufoff) + ldsw + _i * 8192), 16, 0, 0); } while (0)
; #define PG8_LDA(dst, b, h) do { _Pragma("unroll") for (int m = 0; m < 4; ++m) _Pragma("unroll") for (int k = 0; k < 2; ++k) dst[m][k] = *(const LAS bf16x8*)(lds + PG8_SA(b, h) + aoff + m * 2048 + k * 1024); } while (0)
; #define PG8_LDB(dst, b, h) do { _Pragma("unroll") for (int n = 0; n < 2; ++n) _Pragma("unroll") for (int k = 0; k < 2; ++k) dst[n][k] = *(const LAS bf16x8*)(lds + PG8_SB(b, h) + boff + n * 2048 + k * 1024); } while (0)
; #define PG8_MMA(ai, bj, At, Bt) do { __builtin_amdgcn_s_setprio(1); _Pragma("unroll") for (int m = 0; m < 4; ++m) _Pragma("unroll") for (int n = 0; n < 2; ++n) _Pragma("unroll") for (int k = 0; k < 2; ++k) \
;         acc[ai][bj][m][n] = __builtin_amdgcn_mfma_f32_16x16x32_bf16(Bt[n][k], At[m][k], acc[ai][bj][m][n], 0, 0, 0); __builtin_amdgcn_s_setprio(0); } while (0)
; #define PG8_WAIT_V(n) asm volatile("s_waitcnt vmcnt(" #n ")" ::: "memory")
; #define PG8_WAIT_L(n) asm volatile("s_waitcnt lgkmcnt(" #n ")" ::: "memory")
; #define PG8_BAR __builtin_amdgcn_s_barrier()
; #define PG8_SCHED __builtin_amdgcn_sched_barrier(0)
; template <class Epi>
; __device__ __forceinline__ void gemm_phase(LAS unsigned char* lds, const Gemm g, const StaticOrder& S, const Epi& E, int wave) {
;     ...
;             PG8_STAGE(PG8_SB(0, 1), b2 + hstep, voffB);
;             PG8_WAIT_V(6); PG8_BAR; PG8_MMA(1, 1, At, B1); PG8_BAR;
;             PG8_LDB(B0, 1, 0); PG8_SCHED; PG8_LDA(At, 1, 0); PG8_STAGE(PG8_SA(0, 1), a2 + hstep, voffA);
;             PG8_WAIT_L(8); PG8_BAR; PG8_WAIT_L(0); PG8_MMA(0, 0, At, B0); PG8_BAR; PG8_SCHED;
;             PG8_LDB(B1, 1, 1); PG8_STAGE(PG8_SB(1, 0), b3, voffB);
;             PG8_BAR; PG8_WAIT_L(0); PG8_MMA(0, 1, At, B1); PG8_BAR;
;             PG8_LDA(At, 1, 1); PG8_STAGE(PG8_SA(1, 0), a3, voffA);
;             PG8_BAR; PG8_WAIT_L(0); PG8_MMA(1, 0, At, B0); PG8_BAR; PG8_SCHED;
;             PG8_STAGE(PG8_SB(1, 1), b3 + hstep, voffB);
	s_add_u32 s26, s30, 0x40000
	s_addc_u32 s27, s31, 0
	s_add_i32 s63, s56, s39
	v_lshl_add_u64 v[128:129], s[26:27], 0, v[146:147]
	s_mov_b32 m0, s63
	s_nop 0
	global_load_lds_dwordx4 v[128:129], off
	v_lshl_add_u64 v[128:129], s[26:27], 0, v[144:145]
	s_add_i32 m0, s63, 0x2000
	s_nop 0
	global_load_lds_dwordx4 v[128:129], off
	s_waitcnt vmcnt(6)
	s_barrier
	s_setprio 1
	v_mfma_f32_16x16x32_bf16 v[40:43], v[194:197], v[156:159], v[40:43]
	v_mfma_f32_16x16x32_bf16 v[36:39], v[202:205], v[156:159], v[36:39]
	v_mfma_f32_16x16x32_bf16 v[28:31], v[194:197], v[170:173], v[28:31]
	v_mfma_f32_16x16x32_bf16 v[24:27], v[202:205], v[170:173], v[24:27]
	v_mfma_f32_16x16x32_bf16 v[16:19], v[194:197], v[178:181], v[16:19]
	v_mfma_f32_16x16x32_bf16 v[12:15], v[202:205], v[178:181], v[12:15]
	v_mfma_f32_16x16x32_bf16 v[4:7], v[194:197], v[186:189], v[4:7]
	v_mfma_f32_16x16x32_bf16 v[0:3], v[202:205], v[186:189], v[0:3]
	v_mfma_f32_16x16x32_bf16 v[40:43], v[198:201], v[166:169], v[40:43]
	v_mfma_f32_16x16x32_bf16 v[36:39], v[206:209], v[166:169], v[36:39]
	v_mfma_f32_16x16x32_bf16 v[28:31], v[198:201], v[174:177], v[28:31]
	v_mfma_f32_16x16x32_bf16 v[24:27], v[206:209], v[174:177], v[24:27]
	v_mfma_f32_16x16x32_bf16 v[16:19], v[198:201], v[182:185], v[16:19]
	v_mfma_f32_16x16x32_bf16 v[12:15], v[206:209], v[182:185], v[12:15]
	v_mfma_f32_16x16x32_bf16 v[4:7], v[198:201], v[190:193], v[4:7]
	v_mfma_f32_16x16x32_bf16 v[0:3], v[206:209], v[190:193], v[0:3]
	s_setprio 0
	s_add_i32 s63, 0, 0x18000
	v_add_u32_e32 v140, s63, v162
	s_barrier
	ds_read_b128 v[128:131], v140
	ds_read_b128 v[132:135], v140 offset:1024
	ds_read_b128 v[136:139], v140 offset:2048
	ds_read_b128 v[140:143], v140 offset:3072
	s_add_u32 s26, s34, 0x40000
	s_addc_u32 s27, s35, 0
	s_mov_b32 m0, s43
	v_lshl_add_u64 v[194:195], s[26:27], 0, v[146:147]
	ds_read_b128 v[156:159], v164 offset:32768
	ds_read_b128 v[166:169], v164 offset:33792
	ds_read_b128 v[170:173], v164 offset:34816
	ds_read_b128 v[174:177], v164 offset:35840
	ds_read_b128 v[178:181], v164 offset:36864
	ds_read_b128 v[182:185], v164 offset:37888
	ds_read_b128 v[186:189], v164 offset:38912
	ds_read_b128 v[190:193], v164 offset:39936
	global_load_lds_dwordx4 v[194:195], off
	v_lshl_add_u64 v[194:195], s[26:27], 0, v[144:145]
	s_mov_b32 m0, s44
	s_nop 0
	global_load_lds_dwordx4 v[194:195], off
	s_waitcnt lgkmcnt(8)
	s_barrier
	s_waitcnt lgkmcnt(0)
	s_setprio 1
	s_waitcnt lgkmcnt(0)
	v_mfma_f32_16x16x32_bf16 v[124:127], v[128:131], v[156:159], v[124:127]
	v_mfma_f32_16x16x32_bf16 v[120:123], v[136:139], v[156:159], v[120:123]
	v_mfma_f32_16x16x32_bf16 v[116:119], v[128:131], v[170:173], v[116:119]
	v_mfma_f32_16x16x32_bf16 v[112:115], v[136:139], v[170:173], v[112:115]
	v_mfma_f32_16x16x32_bf16 v[108:111], v[128:131], v[178:181], v[108:111]
	v_mfma_f32_16x16x32_bf16 v[96:99], v[136:139], v[178:181], v[96:99]
	v_mfma_f32_16x16x32_bf16 v[84:87], v[128:131], v[186:189], v[84:87]
	v_mfma_f32_16x16x32_bf16 v[72:75], v[136:139], v[186:189], v[72:75]
	v_mfma_f32_16x16x32_bf16 v[124:127], v[132:135], v[166:169], v[124:127]
	v_mfma_f32_16x16x32_bf16 v[120:123], v[140:143], v[166:169], v[120:123]
	v_mfma_f32_16x16x32_bf16 v[116:119], v[132:135], v[174:177], v[116:119]
	v_mfma_f32_16x16x32_bf16 v[112:115], v[140:143], v[174:177], v[112:115]
	v_mfma_f32_16x16x32_bf16 v[108:111], v[132:135], v[182:185], v[108:111]
	v_mfma_f32_16x16x32_bf16 v[96:99], v[140:143], v[182:185], v[96:99]
	v_mfma_f32_16x16x32_bf16 v[84:87], v[132:135], v[190:193], v[84:87]
	v_mfma_f32_16x16x32_bf16 v[72:75], v[140:143], v[190:193], v[72:75]
	s_setprio 0
	s_barrier
	s_add_i32 s34, 0, 0x1c000
	s_add_i32 s26, s63, s39
	v_add_u32_e32 v206, s34, v162
	v_lshl_add_u64 v[160:161], v[160:161], 0, s[6:7]
	s_mov_b32 m0, s26
	ds_read_b128 v[194:197], v206
	ds_read_b128 v[198:201], v206 offset:1024
	ds_read_b128 v[202:205], v206 offset:2048
	ds_read_b128 v[206:209], v206 offset:3072
	global_load_lds_dwordx4 v[160:161], off
	v_lshl_add_u64 v[160:161], v[210:211], 0, s[6:7]
	s_add_i32 m0, s26, 0x2000
	s_nop 0
	global_load_lds_dwordx4 v[160:161], off
	s_barrier
	s_waitcnt lgkmcnt(0)
	s_setprio 1
	s_waitcnt lgkmcnt(0)
	v_mfma_f32_16x16x32_bf16 v[104:107], v[194:197], v[156:159], v[104:107]
	v_mfma_f32_16x16x32_bf16 v[100:103], v[202:205], v[156:159], v[100:103]
	v_mfma_f32_16x16x32_bf16 v[92:95], v[194:197], v[170:173], v[92:95]
	v_mfma_f32_16x16x32_bf16 v[88:91], v[202:205], v[170:173], v[88:91]
	v_mfma_f32_16x16x32_bf16 v[80:83], v[194:197], v[178:181], v[80:83]
	v_mfma_f32_16x16x32_bf16 v[76:79], v[202:205], v[178:181], v[76:79]
	v_mfma_f32_16x16x32_bf16 v[68:71], v[194:197], v[186:189], v[68:71]
	v_mfma_f32_16x16x32_bf16 v[64:67], v[202:205], v[186:189], v[64:67]
	v_mfma_f32_16x16x32_bf16 v[104:107], v[198:201], v[166:169], v[104:107]
	v_mfma_f32_16x16x32_bf16 v[100:103], v[206:209], v[166:169], v[100:103]
	v_mfma_f32_16x16x32_bf16 v[92:95], v[198:201], v[174:177], v[92:95]
	v_mfma_f32_16x16x32_bf16 v[88:91], v[206:209], v[174:177], v[88:91]
	v_mfma_f32_16x16x32_bf16 v[80:83], v[198:201], v[182:185], v[80:83]
	v_mfma_f32_16x16x32_bf16 v[76:79], v[206:209], v[182:185], v[76:79]
	v_mfma_f32_16x16x32_bf16 v[68:71], v[198:201], v[190:193], v[68:71]
	v_mfma_f32_16x16x32_bf16 v[64:67], v[206:209], v[190:193], v[64:67]
	s_setprio 0
	s_mov_b32 m0, s53
	v_lshl_add_u64 v[160:161], v[212:213], 0, s[6:7]
	s_barrier
	ds_read_b128 v[156:159], v164 offset:49152
	ds_read_b128 v[166:169], v164 offset:50176
	ds_read_b128 v[170:173], v164 offset:51200
	ds_read_b128 v[174:177], v164 offset:52224
	ds_read_b128 v[178:181], v164 offset:53248
	ds_read_b128 v[182:185], v164 offset:54272
	ds_read_b128 v[186:189], v164 offset:55296
	ds_read_b128 v[190:193], v164 offset:56320
	global_load_lds_dwordx4 v[160:161], off
	v_lshl_add_u64 v[160:161], v[214:215], 0, s[6:7]
	s_mov_b32 m0, s54
	s_nop 0
	global_load_lds_dwordx4 v[160:161], off
	s_barrier
; #define PG8_STAGE(bufoff, gbase, voff) do { _Pragma("unroll") for (int _i = 0; _i < 2; ++_i) \
;         __builtin_amdgcn_global_load_lds((const unsigned*)((const char*)(gbase) + (voff)[_i]), (LAS unsigned*)(lds + (bufoff) + ldsw + _i * 8192), 16, 0, 0); } while (0)
; #define PG8_MMA(ai, bj, At, Bt) do { __builtin_amdgcn_s_setprio(1); _Pragma("unroll") for (int m = 0; m < 4; ++m) _Pragma("unroll") for (int n = 0; n < 2; ++n) _Pragma("unroll") for (int k = 0; k < 2; ++k) \
;         acc[ai][bj][m][n] = __builtin_amdgcn_mfma_f32_16x16x32_bf16(Bt[n][k], At[m][k], acc[ai][bj][m][n], 0, 0, 0); __builtin_amdgcn_s_setprio(0); } while (0)
; #define PG8_WAIT_V(n) asm volatile("s_waitcnt vmcnt(" #n ")" ::: "memory")
; #define PG8_WAIT_L(n) asm volatile("s_waitcnt lgkmcnt(" #n ")" ::: "memory")
; #define PG8_BAR __builtin_amdgcn_s_barrier()
; template <class Epi>
; __device__ __forceinline__ void gemm_phase(LAS unsigned char* lds, const Gemm g, const StaticOrder& S, const Epi& E, int wave) {
;     ...
;             PG8_BAR; PG8_WAIT_L(0); PG8_MMA(1, 0, At, B0); PG8_BAR; PG8_SCHED;
;             PG8_STAGE(PG8_SB(1, 1), b3 + hstep, voffB);
;             PG8_WAIT_V(6); PG8_BAR; PG8_MMA(1, 1, At, B1); PG8_BAR;
;         }
;     __device__ __forceinline__ void operator()(const f32x4 (&acc)[2][2][4][2], const pg8::Unit& u, int wr, int wc, int, int) const {
;         int ln_; asm volatile("v_mbcnt_lo_u32_b32 %0, -1, 0\n\tv_mbcnt_hi_u32_b32 %0, -1, %0" : "=v"(ln_)); const int fr = ln_ & 15, fq = ln_ >> 4;
;         const int row0 = u.pm * 256 + wr * 64 + fr, col0 = u.pn * 256 + wc * 32 + 4 * fq;
;         const int bi = batch_of(u.pm * 256);
;         const float* base = (u.pm * 256 < NPTOK) ? basep : bases - (size_t)NPTOK * D;
;         f32x4 gv[2][2];
; #pragma unroll
;         for (int bj = 0; bj < 2; ++bj)
; #pragma unroll
;             for (int n = 0; n < 2; ++n) gv[bj][n] = *(const f32x4*)(gate + (size_t)bi * MODW + col0 + bj * HALF + n * 16);
; #pragma unroll
;         for (int ai = 0; ai < 2; ++ai) {
;             f32x4 bv[4][2][2];
; #pragma unroll
;             for (int m = 0; m < 4; ++m) { const size_t off = (size_t)(row0 + ai * HALF + m * 16) * D + col0;
; #pragma unroll
;                 for (int bj = 0; bj < 2; ++bj)
; #pragma unroll
;                     for (int n = 0; n < 2; ++n) bv[m][bj][n] = *(const f32x4*)(base + off + bj * HALF + n * 16); }
	s_waitcnt lgkmcnt(0)
	s_setprio 1
	s_waitcnt lgkmcnt(0)
	v_mfma_f32_16x16x32_bf16 v[60:63], v[128:131], v[156:159], v[60:63]
	v_mfma_f32_16x16x32_bf16 v[56:59], v[136:139], v[156:159], v[56:59]
	v_mfma_f32_16x16x32_bf16 v[52:55], v[128:131], v[170:173], v[52:55]
	v_mfma_f32_16x16x32_bf16 v[48:51], v[136:139], v[170:173], v[48:51]
	v_mfma_f32_16x16x32_bf16 v[44:47], v[128:131], v[178:181], v[44:47]
	v_mfma_f32_16x16x32_bf16 v[32:35], v[136:139], v[178:181], v[32:35]
	v_mfma_f32_16x16x32_bf16 v[20:23], v[128:131], v[186:189], v[20:23]
	v_mfma_f32_16x16x32_bf16 v[8:11], v[136:139], v[186:189], v[8:11]
	v_mfma_f32_16x16x32_bf16 v[60:63], v[132:135], v[166:169], v[60:63]
	v_mfma_f32_16x16x32_bf16 v[56:59], v[140:143], v[166:169], v[56:59]
	v_mfma_f32_16x16x32_bf16 v[52:55], v[132:135], v[174:177], v[52:55]
	v_mfma_f32_16x16x32_bf16 v[48:51], v[140:143], v[174:177], v[48:51]
	v_mfma_f32_16x16x32_bf16 v[44:47], v[132:135], v[182:185], v[44:47]
	v_mfma_f32_16x16x32_bf16 v[32:35], v[140:143], v[182:185], v[32:35]
	v_mfma_f32_16x16x32_bf16 v[20:23], v[132:135], v[190:193], v[20:23]
	v_mfma_f32_16x16x32_bf16 v[8:11], v[140:143], v[190:193], v[8:11]
	s_setprio 0
	s_barrier
	s_add_u32 s26, s30, 0x40080
	s_addc_u32 s27, s31, 0
	s_add_i32 s30, s34, s39
	v_lshl_add_u64 v[128:129], s[26:27], 0, v[146:147]
	s_mov_b32 m0, s30
	s_nop 0
	global_load_lds_dwordx4 v[128:129], off
	v_lshl_add_u64 v[128:129], s[26:27], 0, v[144:145]
	s_add_i32 m0, s30, 0x2000
	s_nop 0
	global_load_lds_dwordx4 v[128:129], off
	s_waitcnt vmcnt(6)
	s_barrier
	s_setprio 1
	v_mfma_f32_16x16x32_bf16 v[40:43], v[194:197], v[156:159], v[40:43]
	v_mfma_f32_16x16x32_bf16 v[36:39], v[202:205], v[156:159], v[36:39]
	v_mfma_f32_16x16x32_bf16 v[28:31], v[194:197], v[170:173], v[28:31]
	v_mfma_f32_16x16x32_bf16 v[24:27], v[202:205], v[170:173], v[24:27]
	v_mfma_f32_16x16x32_bf16 v[16:19], v[194:197], v[178:181], v[16:19]
	v_mfma_f32_16x16x32_bf16 v[12:15], v[202:205], v[178:181], v[12:15]
	v_mfma_f32_16x16x32_bf16 v[4:7], v[194:197], v[186:189], v[4:7]
	v_mfma_f32_16x16x32_bf16 v[0:3], v[202:205], v[186:189], v[0:3]
	v_mfma_f32_16x16x32_bf16 v[40:43], v[198:201], v[166:169], v[40:43]
	v_mfma_f32_16x16x32_bf16 v[36:39], v[206:209], v[166:169], v[36:39]
	v_mfma_f32_16x16x32_bf16 v[28:31], v[198:201], v[174:177], v[28:31]
	v_mfma_f32_16x16x32_bf16 v[24:27], v[206:209], v[174:177], v[24:27]
	v_mfma_f32_16x16x32_bf16 v[16:19], v[198:201], v[182:185], v[16:19]
	v_mfma_f32_16x16x32_bf16 v[12:15], v[206:209], v[182:185], v[12:15]
	v_mfma_f32_16x16x32_bf16 v[4:7], v[198:201], v[190:193], v[4:7]
	v_mfma_f32_16x16x32_bf16 v[0:3], v[206:209], v[190:193], v[0:3]
	s_setprio 0
	s_add_i32 s62, s62, 2
	s_add_u32 s60, s60, 0x100
	s_addc_u32 s61, s61, 0
	s_cmp_gt_u32 s62, 13
	s_mov_b64 s[26:27], s[28:29]
	s_barrier
	s_cbranch_scc0 .LBB0_767
	s_lshl_b32 s17, s24, 8
	s_add_i32 s19, s17, s51
	s_min_i32 s17, s17, 0x10000
	v_mbcnt_lo_u32_b32 v158, -1, 0
	v_mbcnt_hi_u32_b32 v158, -1, v158
	s_lshl_b32 s26, s57, 8
	v_ashrrev_i32_e32 v128, 2, v158
	s_ashr_i32 s17, s17, 11
	s_or_b32 s26, s26, s52
	v_and_b32_e32 v128, -4, v128
	s_mul_hi_i32 s27, s17, 0x6000
	s_mulk_i32 s17, 0x6000
	v_add_u32_e32 v128, s26, v128
	s_add_u32 s26, s46, s17
	v_readlane_b32 s76, v253, 12
	s_addc_u32 s27, s47, s27
	v_ashrrev_i32_e32 v129, 31, v128
	v_and_or_b32 v214, v158, 15, s19
	v_readlane_b32 s77, v253, 13
	v_lshlrev_b64 v[156:157], 2, v[128:129]
	s_cmpk_lt_i32 s24, 0x100
	s_mov_b64 s[60:61], s[76:77]
	v_ashrrev_i32_e32 v215, 31, v214
	v_or_b32_e32 v182, 16, v214
	v_or_b32_e32 v198, 32, v214
	v_lshl_add_u64 v[128:129], s[26:27], 0, v[156:157]
	s_cselect_b32 s27, s61, s50
	s_cselect_b32 s26, s60, s49
	v_lshlrev_b64 v[160:161], 12, v[214:215]
	v_ashrrev_i32_e32 v183, 31, v182
	v_ashrrev_i32_e32 v199, 31, v198
	v_or_b32_e32 v214, 48, v214
	v_lshl_add_u64 v[158:159], s[26:27], 0, v[156:157]
	v_lshlrev_b64 v[230:231], 12, v[182:183]
	v_lshlrev_b64 v[232:233], 12, v[198:199]
	v_ashrrev_i32_e32 v215, 31, v214
	v_lshl_add_u64 v[178:179], v[158:159], 0, v[160:161]
	v_lshl_add_u64 v[194:195], v[158:159], 0, v[230:231]
	v_lshl_add_u64 v[210:211], v[158:159], 0, v[232:233]
	v_lshlrev_b64 v[234:235], 12, v[214:215]
	global_load_dwordx4 v[140:143], v[128:129], off
	global_load_dwordx4 v[136:139], v[128:129], off offset:64
	global_load_dwordx4 v[132:135], v[128:129], off offset:512
	s_nop 0
	global_load_dwordx4 v[128:131], v[128:129], off offset:576
	s_nop 0
	global_load_dwordx4 v[166:169], v[178:179], off
	global_load_dwordx4 v[170:173], v[178:179], off offset:64
	global_load_dwordx4 v[174:177], v[178:179], off offset:512
	s_nop 0
	global_load_dwordx4 v[178:181], v[178:179], off offset:576
	s_nop 0
	global_load_dwordx4 v[182:185], v[194:195], off
	global_load_dwordx4 v[186:189], v[194:195], off offset:64
	global_load_dwordx4 v[190:193], v[194:195], off offset:512
	s_nop 0
	global_load_dwordx4 v[194:197], v[194:195], off offset:576
	s_nop 0
	global_load_dwordx4 v[198:201], v[210:211], off
	global_load_dwordx4 v[202:205], v[210:211], off offset:64
	global_load_dwordx4 v[206:209], v[210:211], off offset:512
	s_nop 0
	global_load_dwordx4 v[210:213], v[210:211], off offset:576
	v_lshl_add_u64 v[226:227], v[158:159], 0, v[234:235]
	global_load_dwordx4 v[214:217], v[226:227], off
	global_load_dwordx4 v[218:221], v[226:227], off offset:64
	global_load_dwordx4 v[222:225], v[226:227], off offset:512
	s_nop 0
	global_load_dwordx4 v[226:229], v[226:227], off offset:576
	v_readlane_b32 s28, v253, 8
	v_readlane_b32 s29, v253, 9
	s_and_b64 vcc, exec, s[0:1]
	s_mov_b32 s57, s16
	v_lshl_add_u64 v[236:237], s[28:29], 0, v[160:161]
	v_lshl_add_u64 v[232:233], s[28:29], 0, v[232:233]
	v_lshl_add_u64 v[236:237], v[236:237], 0, v[156:157]
	v_lshl_add_u64 v[230:231], s[28:29], 0, v[230:231]
	v_lshl_add_u64 v[232:233], v[232:233], 0, v[156:157]
	v_lshl_add_u64 v[230:231], v[230:231], 0, v[156:157]
	s_mov_b32 s24, s18
	s_mov_b64 s[26:27], s[20:21]
	v_readlane_b32 s78, v253, 14
	v_readlane_b32 s79, v253, 15
	v_readlane_b32 s80, v253, 16
	v_readlane_b32 s81, v253, 17
	v_readlane_b32 s82, v253, 18
	v_readlane_b32 s83, v253, 19
	v_readlane_b32 s84, v253, 20
	v_readlane_b32 s85, v253, 21
	v_readlane_b32 s86, v253, 22
	v_readlane_b32 s87, v253, 23
	v_readlane_b32 s88, v253, 24
	v_readlane_b32 s89, v253, 25
	v_readlane_b32 s90, v253, 26
	v_readlane_b32 s91, v253, 27
	v_readlane_b32 s30, v253, 10
	v_readlane_b32 s31, v253, 11
	s_waitcnt vmcnt(12)
;     __device__ __forceinline__ void operator()(const f32x4 (&acc)[2][2][4][2], const pg8::Unit& u, int wr, int wc, int, int) const {
;     ...
;         for (int ai = 0; ai < 2; ++ai) {
;             f32x4 bv[4][2][2];
; #pragma unroll
;             for (int m = 0; m < 4; ++m) { const size_t off = (size_t)(row0 + ai * HALF + m * 16) * D + col0;
; #pragma unroll
;                 for (int bj = 0; bj < 2; ++bj)
; #pragma unroll
;                     for (int n = 0; n < 2; ++n) bv[m][bj][n] = *(const f32x4*)(base + off + bj * HALF + n * 16); }
; #pragma unroll
;             for (int m = 0; m < 4; ++m) { const size_t off = (size_t)(row0 + ai * HALF + m * 16) * D + col0;
; #pragma unroll
;                 for (int bj = 0; bj < 2; ++bj)
; #pragma unroll
;                     for (int n = 0; n < 2; ++n) *(f32x4*)(out + off + bj * HALF + n * 16) = bv[m][bj][n] + gv[bj][n] * acc[ai][bj][m][n]; }
	v_pk_fma_f32 v[126:127], v[126:127], v[142:143], v[168:169]
	v_pk_fma_f32 v[124:125], v[124:125], v[140:141], v[166:167]
	v_pk_fma_f32 v[122:123], v[122:123], v[138:139], v[172:173]
	v_pk_fma_f32 v[120:121], v[120:121], v[136:137], v[170:171]
	v_pk_fma_f32 v[106:107], v[106:107], v[134:135], v[176:177]
	v_pk_fma_f32 v[104:105], v[104:105], v[132:133], v[174:175]
	v_pk_fma_f32 v[102:103], v[102:103], v[130:131], v[180:181]
	v_pk_fma_f32 v[100:101], v[100:101], v[128:129], v[178:179]
	v_lshl_add_u64 v[238:239], v[160:161], 0, s[8:9]
	v_lshl_add_u64 v[238:239], v[158:159], 0, v[238:239]
	global_load_dwordx4 v[166:169], v[238:239], off
	global_load_dwordx4 v[170:173], v[238:239], off offset:64
	global_load_dwordx4 v[174:177], v[238:239], off offset:512
	global_load_dwordx4 v[178:181], v[238:239], off offset:576
	s_waitcnt vmcnt(12)
	v_pk_fma_f32 v[118:119], v[118:119], v[142:143], v[184:185]
	v_pk_fma_f32 v[116:117], v[116:117], v[140:141], v[182:183]
	v_pk_fma_f32 v[114:115], v[114:115], v[138:139], v[188:189]
	v_pk_fma_f32 v[112:113], v[112:113], v[136:137], v[186:187]
	v_pk_fma_f32 v[94:95], v[94:95], v[134:135], v[192:193]
	v_pk_fma_f32 v[92:93], v[92:93], v[132:133], v[190:191]
	v_pk_fma_f32 v[90:91], v[90:91], v[130:131], v[196:197]
	v_pk_fma_f32 v[88:89], v[88:89], v[128:129], v[194:195]
	v_lshl_add_u64 v[240:241], v[160:161], 0, s[10:11]
	v_lshl_add_u64 v[240:241], v[158:159], 0, v[240:241]
	global_load_dwordx4 v[182:185], v[240:241], off
	global_load_dwordx4 v[186:189], v[240:241], off offset:64
	global_load_dwordx4 v[190:193], v[240:241], off offset:512
	global_load_dwordx4 v[194:197], v[240:241], off offset:576
	s_waitcnt vmcnt(12)
	v_pk_fma_f32 v[110:111], v[110:111], v[142:143], v[200:201]
	v_pk_fma_f32 v[108:109], v[108:109], v[140:141], v[198:199]
	v_pk_fma_f32 v[98:99], v[98:99], v[138:139], v[204:205]
	v_pk_fma_f32 v[96:97], v[96:97], v[136:137], v[202:203]
	v_pk_fma_f32 v[82:83], v[82:83], v[134:135], v[208:209]
	v_pk_fma_f32 v[80:81], v[80:81], v[132:133], v[206:207]
	v_pk_fma_f32 v[78:79], v[78:79], v[130:131], v[212:213]
	v_pk_fma_f32 v[76:77], v[76:77], v[128:129], v[210:211]
	v_lshl_add_u64 v[238:239], v[160:161], 0, s[12:13]
	v_lshl_add_u64 v[238:239], v[158:159], 0, v[238:239]
	global_load_dwordx4 v[198:201], v[238:239], off
	global_load_dwordx4 v[202:205], v[238:239], off offset:64
	global_load_dwordx4 v[206:209], v[238:239], off offset:512
	global_load_dwordx4 v[210:213], v[238:239], off offset:576
	s_waitcnt vmcnt(12)
	v_pk_fma_f32 v[86:87], v[86:87], v[142:143], v[216:217]
	v_pk_fma_f32 v[84:85], v[84:85], v[140:141], v[214:215]
	v_pk_fma_f32 v[74:75], v[74:75], v[138:139], v[220:221]
	v_pk_fma_f32 v[72:73], v[72:73], v[136:137], v[218:219]
	v_pk_fma_f32 v[70:71], v[70:71], v[134:135], v[224:225]
	v_pk_fma_f32 v[68:69], v[68:69], v[132:133], v[222:223]
	v_pk_fma_f32 v[66:67], v[66:67], v[130:131], v[228:229]
	v_pk_fma_f32 v[64:65], v[64:65], v[128:129], v[226:227]
	v_lshl_add_u64 v[240:241], v[160:161], 0, s[14:15]
	v_lshl_add_u64 v[240:241], v[158:159], 0, v[240:241]
	global_load_dwordx4 v[214:217], v[240:241], off
	global_load_dwordx4 v[218:221], v[240:241], off offset:64
	global_load_dwordx4 v[222:225], v[240:241], off offset:512
	global_load_dwordx4 v[226:229], v[240:241], off offset:576
	global_store_dwordx4 v[236:237], v[124:127], off
	global_store_dwordx4 v[236:237], v[120:123], off offset:64
	global_store_dwordx4 v[236:237], v[104:107], off offset:512
	global_store_dwordx4 v[236:237], v[100:103], off offset:576
	global_store_dwordx4 v[230:231], v[116:119], off
	global_store_dwordx4 v[230:231], v[112:115], off offset:64
	global_store_dwordx4 v[230:231], v[92:95], off offset:512
	global_store_dwordx4 v[230:231], v[88:91], off offset:576
	global_store_dwordx4 v[232:233], v[108:111], off
	global_store_dwordx4 v[232:233], v[96:99], off offset:64
	global_store_dwordx4 v[232:233], v[80:83], off offset:512
	global_store_dwordx4 v[232:233], v[76:79], off offset:576
	v_lshl_add_u64 v[244:245], s[28:29], 0, v[234:235]
	v_lshl_add_u64 v[244:245], v[244:245], 0, v[156:157]
	global_store_dwordx4 v[244:245], v[84:87], off
	global_store_dwordx4 v[244:245], v[72:75], off offset:64
	global_store_dwordx4 v[244:245], v[68:71], off offset:512
	global_store_dwordx4 v[244:245], v[64:67], off offset:576
	v_lshl_add_u64 v[246:247], v[160:161], 0, s[8:9]
	v_lshl_add_u64 v[246:247], s[28:29], 0, v[246:247]
	v_lshl_add_u64 v[246:247], v[246:247], 0, v[156:157]
	s_waitcnt vmcnt(28)
;     __device__ __forceinline__ void operator()(const f32x4 (&acc)[2][2][4][2], const pg8::Unit& u, int wr, int wc, int, int) const {
;     ...
;         for (int ai = 0; ai < 2; ++ai) {
;             f32x4 bv[4][2][2];
; #pragma unroll
;             for (int m = 0; m < 4; ++m) { const size_t off = (size_t)(row0 + ai * HALF + m * 16) * D + col0;
; #pragma unroll
;                 for (int bj = 0; bj < 2; ++bj)
; #pragma unroll
;                     for (int n = 0; n < 2; ++n) bv[m][bj][n] = *(const f32x4*)(base + off + bj * HALF + n * 16); }
; #pragma unroll
;             for (int m = 0; m < 4; ++m) { const size_t off = (size_t)(row0 + ai * HALF + m * 16) * D + col0;
; #pragma unroll
;                 for (int bj = 0; bj < 2; ++bj)
; #pragma unroll
;                     for (int n = 0; n < 2; ++n) *(f32x4*)(out + off + bj * HALF + n * 16) = bv[m][bj][n] + gv[bj][n] * acc[ai][bj][m][n]; }
	v_pk_fma_f32 v[62:63], v[62:63], v[142:143], v[168:169]
	v_pk_fma_f32 v[60:61], v[60:61], v[140:141], v[166:167]
	v_pk_fma_f32 v[58:59], v[58:59], v[138:139], v[172:173]
	v_pk_fma_f32 v[56:57], v[56:57], v[136:137], v[170:171]
	v_pk_fma_f32 v[42:43], v[42:43], v[134:135], v[176:177]
	v_pk_fma_f32 v[40:41], v[40:41], v[132:133], v[174:175]
	v_pk_fma_f32 v[38:39], v[38:39], v[130:131], v[180:181]
	v_pk_fma_f32 v[36:37], v[36:37], v[128:129], v[178:179]
	global_store_dwordx4 v[246:247], v[60:63], off
	global_store_dwordx4 v[246:247], v[56:59], off offset:64
	global_store_dwordx4 v[246:247], v[40:43], off offset:512
	global_store_dwordx4 v[246:247], v[36:39], off offset:576
	v_lshl_add_u64 v[248:249], v[160:161], 0, s[10:11]
	v_lshl_add_u64 v[248:249], s[28:29], 0, v[248:249]
	v_lshl_add_u64 v[248:249], v[248:249], 0, v[156:157]
	s_waitcnt vmcnt(28)
	v_pk_fma_f32 v[54:55], v[54:55], v[142:143], v[184:185]
	v_pk_fma_f32 v[52:53], v[52:53], v[140:141], v[182:183]
	v_pk_fma_f32 v[50:51], v[50:51], v[138:139], v[188:189]
	v_pk_fma_f32 v[48:49], v[48:49], v[136:137], v[186:187]
	v_pk_fma_f32 v[30:31], v[30:31], v[134:135], v[192:193]
	v_pk_fma_f32 v[28:29], v[28:29], v[132:133], v[190:191]
	v_pk_fma_f32 v[26:27], v[26:27], v[130:131], v[196:197]
	v_pk_fma_f32 v[24:25], v[24:25], v[128:129], v[194:195]
	global_store_dwordx4 v[248:249], v[52:55], off
	global_store_dwordx4 v[248:249], v[48:51], off offset:64
	global_store_dwordx4 v[248:249], v[28:31], off offset:512
	global_store_dwordx4 v[248:249], v[24:27], off offset:576
	v_lshl_add_u64 v[246:247], v[160:161], 0, s[12:13]
	v_lshl_add_u64 v[246:247], s[28:29], 0, v[246:247]
	v_lshl_add_u64 v[246:247], v[246:247], 0, v[156:157]
	s_waitcnt vmcnt(28)
	v_pk_fma_f32 v[46:47], v[46:47], v[142:143], v[200:201]
	v_pk_fma_f32 v[44:45], v[44:45], v[140:141], v[198:199]
	v_pk_fma_f32 v[34:35], v[34:35], v[138:139], v[204:205]
	v_pk_fma_f32 v[32:33], v[32:33], v[136:137], v[202:203]
	v_pk_fma_f32 v[18:19], v[18:19], v[134:135], v[208:209]
	v_pk_fma_f32 v[16:17], v[16:17], v[132:133], v[206:207]
	v_pk_fma_f32 v[14:15], v[14:15], v[130:131], v[212:213]
	v_pk_fma_f32 v[12:13], v[12:13], v[128:129], v[210:211]
	global_store_dwordx4 v[246:247], v[44:47], off
	global_store_dwordx4 v[246:247], v[32:35], off offset:64
	global_store_dwordx4 v[246:247], v[16:19], off offset:512
	global_store_dwordx4 v[246:247], v[12:15], off offset:576
	v_lshl_add_u64 v[248:249], v[160:161], 0, s[14:15]
	v_lshl_add_u64 v[248:249], s[28:29], 0, v[248:249]
	v_lshl_add_u64 v[248:249], v[248:249], 0, v[156:157]
	s_waitcnt vmcnt(28)
	v_pk_fma_f32 v[22:23], v[22:23], v[142:143], v[216:217]
	v_pk_fma_f32 v[20:21], v[20:21], v[140:141], v[214:215]
	v_pk_fma_f32 v[10:11], v[10:11], v[138:139], v[220:221]
	v_pk_fma_f32 v[8:9], v[8:9], v[136:137], v[218:219]
	v_pk_fma_f32 v[6:7], v[6:7], v[134:135], v[224:225]
	v_pk_fma_f32 v[4:5], v[4:5], v[132:133], v[222:223]
	v_pk_fma_f32 v[2:3], v[2:3], v[130:131], v[228:229]
	v_pk_fma_f32 v[0:1], v[0:1], v[128:129], v[226:227]
	s_mov_b64 s[28:29], s[22:23]
	global_store_dwordx4 v[248:249], v[20:23], off
	global_store_dwordx4 v[248:249], v[8:11], off offset:64
	global_store_dwordx4 v[248:249], v[4:7], off offset:512
	global_store_dwordx4 v[248:249], v[0:3], off offset:576
	s_cbranch_vccz .LBB0_764
	s_waitcnt vmcnt(0)
	s_cmpk_gt_u32 s3, 0xff
	s_cbranch_scc1 .LBB0_771
	s_barrier

; #define PG8_STAGE(bufoff, gbase, voff) do { _Pragma("unroll") for (int _i = 0; _i < 2; ++_i) \
;         __builtin_amdgcn_global_load_lds((const unsigned*)((const char*)(gbase) + (voff)[_i]), (LAS unsigned*)(lds + (bufoff) + ldsw + _i * 8192), 16, 0, 0); } while (0)
; #define PG8_LDA(dst, b, h) do { _Pragma("unroll") for (int m = 0; m < 4; ++m) _Pragma("unroll") for (int k = 0; k < 2; ++k) dst[m][k] = *(const LAS bf16x8*)(lds + PG8_SA(b, h) + aoff + m * 2048 + k * 1024); } while (0)
; #define PG8_LDB(dst, b, h) do { _Pragma("unroll") for (int n = 0; n < 2; ++n) _Pragma("unroll") for (int k = 0; k < 2; ++k) dst[n][k] = *(const LAS bf16x8*)(lds + PG8_SB(b, h) + boff + n * 2048 + k * 1024); } while (0)
; #define PG8_WAIT_V(n) asm volatile("s_waitcnt vmcnt(" #n ")" ::: "memory")
; #define PG8_WAIT_L(n) asm volatile("s_waitcnt lgkmcnt(" #n ")" ::: "memory")
; #define PG8_BAR __builtin_amdgcn_s_barrier()
; #define PG8_SCHED __builtin_amdgcn_sched_barrier(0)
; template <class Epi>
; __device__ __forceinline__ void gemm_phase(LAS unsigned char* lds, const Gemm g, const StaticOrder& S, const Epi& E, int wave) {
;     ...
;         for (int t = 0; t < nt; t += 2) {
;             const bool last = (t == nt - 2);
;             const char* a1 = cA + (size_t)(t + 1) * kstep;
;             const char* a2 = last ? nA : cA + (size_t)(t + 2) * kstep; const char* b2 = last ? nB : cB + (size_t)(t + 2) * kstep;
;             const char* a3 = a2 + kstep; const char* b3 = b2 + kstep;
;             PG8_LDB(B0, 0, 0); PG8_SCHED; PG8_LDA(At, 0, 0); PG8_STAGE(PG8_SA(1, 1), a1 + hstep, voffA);
;             PG8_WAIT_L(8); PG8_BAR; PG8_WAIT_L(0); PG8_MMA(0, 0, At, B0); PG8_BAR; PG8_SCHED;
;             PG8_LDB(B1, 0, 1); PG8_STAGE(PG8_SB(0, 0), b2, voffB);
;             PG8_BAR; PG8_WAIT_L(0); PG8_MMA(0, 1, At, B1); PG8_BAR;
;             PG8_LDA(At, 0, 1); PG8_STAGE(PG8_SA(0, 0), a2, voffA);
;             PG8_BAR; PG8_WAIT_L(0); PG8_MMA(1, 0, At, B0); PG8_BAR; PG8_SCHED;
;             PG8_STAGE(PG8_SB(0, 1), b2 + hstep, voffB);
;             PG8_WAIT_V(6); PG8_BAR; PG8_MMA(1, 1, At, B1); PG8_BAR;
;             PG8_LDB(B0, 1, 0); PG8_SCHED; PG8_LDA(At, 1, 0); PG8_STAGE(PG8_SA(0, 1), a2 + hstep, voffA);
;             PG8_WAIT_L(8); PG8_BAR; PG8_WAIT_L(0); PG8_MMA(0, 0, At, B0); PG8_BAR; PG8_SCHED;
.LBB0_889:
	ds_read_b128 v[96:99], v163
	ds_read_b128 v[108:111], v163 offset:1024
	ds_read_b128 v[120:123], v163 offset:2048
	ds_read_b128 v[132:135], v163 offset:3072
	s_add_u32 s22, s20, 0x100
	s_addc_u32 s23, s21, 0
	s_cmp_eq_u32 s54, 40
	s_cselect_b32 s27, s7, s23
	s_cselect_b32 s26, s6, s22
	s_cselect_b32 s25, s5, s53
	s_cselect_b32 s24, s4, s52
	v_lshl_add_u64 v[160:161], s[20:21], 0, v[148:149]
	s_add_i32 m0, s34, 0xc000
	ds_read_b128 v[156:159], v164
	ds_read_b128 v[166:169], v164 offset:1024
	ds_read_b128 v[170:173], v164 offset:2048
	ds_read_b128 v[174:177], v164 offset:3072
	ds_read_b128 v[178:181], v164 offset:4096
	ds_read_b128 v[182:185], v164 offset:5120
	ds_read_b128 v[186:189], v164 offset:6144
	ds_read_b128 v[190:193], v164 offset:7168
	global_load_lds_dwordx4 v[160:161], off
	v_lshl_add_u64 v[160:161], s[20:21], 0, v[150:151]
	s_add_i32 m0, s34, 0xe000
	s_nop 0
	global_load_lds_dwordx4 v[160:161], off
	s_waitcnt lgkmcnt(8)
	s_barrier
	s_waitcnt lgkmcnt(0)
	s_setprio 1
	s_waitcnt lgkmcnt(0)
	v_mfma_f32_16x16x32_bf16 v[140:143], v[96:99], v[156:159], v[140:143]
	v_mfma_f32_16x16x32_bf16 v[136:139], v[120:123], v[156:159], v[136:139]
	v_mfma_f32_16x16x32_bf16 v[128:131], v[96:99], v[170:173], v[128:131]
	v_mfma_f32_16x16x32_bf16 v[124:127], v[120:123], v[170:173], v[124:127]
	v_mfma_f32_16x16x32_bf16 v[112:115], v[96:99], v[178:181], v[112:115]
	v_mfma_f32_16x16x32_bf16 v[100:103], v[120:123], v[178:181], v[100:103]
	v_mfma_f32_16x16x32_bf16 v[88:91], v[96:99], v[186:189], v[88:91]
	v_mfma_f32_16x16x32_bf16 v[80:83], v[120:123], v[186:189], v[80:83]
	v_mfma_f32_16x16x32_bf16 v[140:143], v[108:111], v[166:169], v[140:143]
	v_mfma_f32_16x16x32_bf16 v[136:139], v[132:135], v[166:169], v[136:139]
	v_mfma_f32_16x16x32_bf16 v[128:131], v[108:111], v[174:177], v[128:131]
	v_mfma_f32_16x16x32_bf16 v[124:127], v[132:135], v[174:177], v[124:127]
	v_mfma_f32_16x16x32_bf16 v[112:115], v[108:111], v[182:185], v[112:115]
	v_mfma_f32_16x16x32_bf16 v[100:103], v[132:135], v[182:185], v[100:103]
	v_mfma_f32_16x16x32_bf16 v[88:91], v[108:111], v[190:193], v[88:91]
	v_mfma_f32_16x16x32_bf16 v[80:83], v[132:135], v[190:193], v[80:83]
	s_setprio 0
	s_barrier
	s_add_i32 s20, s46, s30
	v_lshl_add_u64 v[160:161], s[24:25], 0, v[146:147]
	s_mov_b32 m0, s20
	ds_read_b128 v[194:197], v165
	ds_read_b128 v[198:201], v165 offset:1024
	ds_read_b128 v[202:205], v165 offset:2048
	ds_read_b128 v[206:209], v165 offset:3072
	global_load_lds_dwordx4 v[160:161], off
	v_lshl_add_u64 v[210:211], s[24:25], 0, v[144:145]
	s_add_i32 m0, s20, 0x2000
	s_nop 0
	global_load_lds_dwordx4 v[210:211], off
	s_barrier
	s_waitcnt lgkmcnt(0)
	s_setprio 1
	s_waitcnt lgkmcnt(0)
	v_mfma_f32_16x16x32_bf16 v[116:119], v[194:197], v[156:159], v[116:119]
	v_mfma_f32_16x16x32_bf16 v[104:107], v[202:205], v[156:159], v[104:107]
	v_mfma_f32_16x16x32_bf16 v[92:95], v[194:197], v[170:173], v[92:95]
	v_mfma_f32_16x16x32_bf16 v[84:87], v[202:205], v[170:173], v[84:87]
	v_mfma_f32_16x16x32_bf16 v[76:79], v[194:197], v[178:181], v[76:79]
	v_mfma_f32_16x16x32_bf16 v[72:75], v[202:205], v[178:181], v[72:75]
	v_mfma_f32_16x16x32_bf16 v[68:71], v[194:197], v[186:189], v[68:71]
	v_mfma_f32_16x16x32_bf16 v[64:67], v[202:205], v[186:189], v[64:67]
	v_mfma_f32_16x16x32_bf16 v[116:119], v[198:201], v[166:169], v[116:119]
	v_mfma_f32_16x16x32_bf16 v[104:107], v[206:209], v[166:169], v[104:107]
	v_mfma_f32_16x16x32_bf16 v[92:95], v[198:201], v[174:177], v[92:95]
	v_mfma_f32_16x16x32_bf16 v[84:87], v[206:209], v[174:177], v[84:87]
	v_mfma_f32_16x16x32_bf16 v[76:79], v[198:201], v[182:185], v[76:79]
	v_mfma_f32_16x16x32_bf16 v[72:75], v[206:209], v[182:185], v[72:75]
	v_mfma_f32_16x16x32_bf16 v[68:71], v[198:201], v[190:193], v[68:71]
	v_mfma_f32_16x16x32_bf16 v[64:67], v[206:209], v[190:193], v[64:67]
	s_setprio 0
	s_mov_b32 m0, s34
	v_lshl_add_u64 v[212:213], s[26:27], 0, v[146:147]
	s_barrier
	ds_read_b128 v[156:159], v164 offset:16384
	ds_read_b128 v[166:169], v164 offset:17408
	ds_read_b128 v[170:173], v164 offset:18432
	ds_read_b128 v[174:177], v164 offset:19456
	ds_read_b128 v[178:181], v164 offset:20480
	ds_read_b128 v[182:185], v164 offset:21504
	ds_read_b128 v[186:189], v164 offset:22528
	ds_read_b128 v[190:193], v164 offset:23552
	global_load_lds_dwordx4 v[212:213], off
	v_lshl_add_u64 v[214:215], s[26:27], 0, v[144:145]
	s_mov_b32 m0, s35
	s_nop 0
	global_load_lds_dwordx4 v[214:215], off
	s_barrier
	s_waitcnt lgkmcnt(0)
	s_setprio 1
	s_waitcnt lgkmcnt(0)
	v_mfma_f32_16x16x32_bf16 v[60:63], v[96:99], v[156:159], v[60:63]
	v_mfma_f32_16x16x32_bf16 v[56:59], v[120:123], v[156:159], v[56:59]
	v_mfma_f32_16x16x32_bf16 v[52:55], v[96:99], v[170:173], v[52:55]
	v_mfma_f32_16x16x32_bf16 v[44:47], v[120:123], v[170:173], v[44:47]
	v_mfma_f32_16x16x32_bf16 v[36:39], v[96:99], v[178:181], v[36:39]
	v_mfma_f32_16x16x32_bf16 v[28:31], v[120:123], v[178:181], v[28:31]
	v_mfma_f32_16x16x32_bf16 v[20:23], v[96:99], v[186:189], v[20:23]
	v_mfma_f32_16x16x32_bf16 v[8:11], v[120:123], v[186:189], v[8:11]
	v_mfma_f32_16x16x32_bf16 v[60:63], v[108:111], v[166:169], v[60:63]
	v_mfma_f32_16x16x32_bf16 v[56:59], v[132:135], v[166:169], v[56:59]
	v_mfma_f32_16x16x32_bf16 v[52:55], v[108:111], v[174:177], v[52:55]
	v_mfma_f32_16x16x32_bf16 v[44:47], v[132:135], v[174:177], v[44:47]
	v_mfma_f32_16x16x32_bf16 v[36:39], v[108:111], v[182:185], v[36:39]
	v_mfma_f32_16x16x32_bf16 v[28:31], v[132:135], v[182:185], v[28:31]
	v_mfma_f32_16x16x32_bf16 v[20:23], v[108:111], v[190:193], v[20:23]
	v_mfma_f32_16x16x32_bf16 v[8:11], v[132:135], v[190:193], v[8:11]
	s_setprio 0
	s_barrier
; #define PG8_STAGE(bufoff, gbase, voff) do { _Pragma("unroll") for (int _i = 0; _i < 2; ++_i) \
;         __builtin_amdgcn_global_load_lds((const unsigned*)((const char*)(gbase) + (voff)[_i]), (LAS unsigned*)(lds + (bufoff) + ldsw + _i * 8192), 16, 0, 0); } while (0)
; #define PG8_LDA(dst, b, h) do { _Pragma("unroll") for (int m = 0; m < 4; ++m) _Pragma("unroll") for (int k = 0; k < 2; ++k) dst[m][k] = *(const LAS bf16x8*)(lds + PG8_SA(b, h) + aoff + m * 2048 + k * 1024); } while (0)
; #define PG8_LDB(dst, b, h) do { _Pragma("unroll") for (int n = 0; n < 2; ++n) _Pragma("unroll") for (int k = 0; k < 2; ++k) dst[n][k] = *(const LAS bf16x8*)(lds + PG8_SB(b, h) + boff + n * 2048 + k * 1024); } while (0)
; #define PG8_MMA(ai, bj, At, Bt) do { __builtin_amdgcn_s_setprio(1); _Pragma("unroll") for (int m = 0; m < 4; ++m) _Pragma("unroll") for (int n = 0; n < 2; ++n) _Pragma("unroll") for (int k = 0; k < 2; ++k) \
;         acc[ai][bj][m][n] = __builtin_amdgcn_mfma_f32_16x16x32_bf16(Bt[n][k], At[m][k], acc[ai][bj][m][n], 0, 0, 0); __builtin_amdgcn_s_setprio(0); } while (0)
; #define PG8_WAIT_V(n) asm volatile("s_waitcnt vmcnt(" #n ")" ::: "memory")
; #define PG8_WAIT_L(n) asm volatile("s_waitcnt lgkmcnt(" #n ")" ::: "memory")
; #define PG8_BAR __builtin_amdgcn_s_barrier()
; #define PG8_SCHED __builtin_amdgcn_sched_barrier(0)
; template <class Epi>
; __device__ __forceinline__ void gemm_phase(LAS unsigned char* lds, const Gemm g, const StaticOrder& S, const Epi& E, int wave) {
;     ...
;             PG8_STAGE(PG8_SB(0, 1), b2 + hstep, voffB);
;             PG8_WAIT_V(6); PG8_BAR; PG8_MMA(1, 1, At, B1); PG8_BAR;
;             PG8_LDB(B0, 1, 0); PG8_SCHED; PG8_LDA(At, 1, 0); PG8_STAGE(PG8_SA(0, 1), a2 + hstep, voffA);
;             PG8_WAIT_L(8); PG8_BAR; PG8_WAIT_L(0); PG8_MMA(0, 0, At, B0); PG8_BAR; PG8_SCHED;
;             PG8_LDB(B1, 1, 1); PG8_STAGE(PG8_SB(1, 0), b3, voffB);
;             PG8_BAR; PG8_WAIT_L(0); PG8_MMA(0, 1, At, B1); PG8_BAR;
;             PG8_LDA(At, 1, 1); PG8_STAGE(PG8_SA(1, 0), a3, voffA);
;             PG8_BAR; PG8_WAIT_L(0); PG8_MMA(1, 0, At, B0); PG8_BAR; PG8_SCHED;
;             PG8_STAGE(PG8_SB(1, 1), b3 + hstep, voffB);
	s_add_u32 s20, s24, 0xb0000
	s_addc_u32 s21, s25, 0
	s_add_i32 s55, s47, s30
	v_lshl_add_u64 v[96:97], s[20:21], 0, v[146:147]
	s_mov_b32 m0, s55
	s_nop 0
	global_load_lds_dwordx4 v[96:97], off
	v_lshl_add_u64 v[96:97], s[20:21], 0, v[144:145]
	s_add_i32 m0, s55, 0x2000
	s_nop 0
	global_load_lds_dwordx4 v[96:97], off
	s_waitcnt vmcnt(6)
	s_barrier
	s_setprio 1
	v_mfma_f32_16x16x32_bf16 v[48:51], v[194:197], v[156:159], v[48:51]
	v_mfma_f32_16x16x32_bf16 v[40:43], v[202:205], v[156:159], v[40:43]
	v_mfma_f32_16x16x32_bf16 v[32:35], v[194:197], v[170:173], v[32:35]
	v_mfma_f32_16x16x32_bf16 v[24:27], v[202:205], v[170:173], v[24:27]
	v_mfma_f32_16x16x32_bf16 v[16:19], v[194:197], v[178:181], v[16:19]
	v_mfma_f32_16x16x32_bf16 v[12:15], v[202:205], v[178:181], v[12:15]
	v_mfma_f32_16x16x32_bf16 v[4:7], v[194:197], v[186:189], v[4:7]
	v_mfma_f32_16x16x32_bf16 v[0:3], v[202:205], v[186:189], v[0:3]
	v_mfma_f32_16x16x32_bf16 v[48:51], v[198:201], v[166:169], v[48:51]
	v_mfma_f32_16x16x32_bf16 v[40:43], v[206:209], v[166:169], v[40:43]
	v_mfma_f32_16x16x32_bf16 v[32:35], v[198:201], v[174:177], v[32:35]
	v_mfma_f32_16x16x32_bf16 v[24:27], v[206:209], v[174:177], v[24:27]
	v_mfma_f32_16x16x32_bf16 v[16:19], v[198:201], v[182:185], v[16:19]
	v_mfma_f32_16x16x32_bf16 v[12:15], v[206:209], v[182:185], v[12:15]
	v_mfma_f32_16x16x32_bf16 v[4:7], v[198:201], v[190:193], v[4:7]
	v_mfma_f32_16x16x32_bf16 v[0:3], v[206:209], v[190:193], v[0:3]
	s_setprio 0
	s_add_i32 s55, 0, 0x18000
	v_add_u32_e32 v132, s55, v162
	s_barrier
	ds_read_b128 v[96:99], v132
	ds_read_b128 v[108:111], v132 offset:1024
	ds_read_b128 v[120:123], v132 offset:2048
	ds_read_b128 v[132:135], v132 offset:3072
	s_add_u32 s20, s26, 0xb0000
	s_addc_u32 s21, s27, 0
	s_mov_b32 m0, s36
	v_lshl_add_u64 v[194:195], s[20:21], 0, v[146:147]
	ds_read_b128 v[156:159], v164 offset:32768
	ds_read_b128 v[166:169], v164 offset:33792
	ds_read_b128 v[170:173], v164 offset:34816
	ds_read_b128 v[174:177], v164 offset:35840
	ds_read_b128 v[178:181], v164 offset:36864
	ds_read_b128 v[182:185], v164 offset:37888
	ds_read_b128 v[186:189], v164 offset:38912
	ds_read_b128 v[190:193], v164 offset:39936
	global_load_lds_dwordx4 v[194:195], off
	v_lshl_add_u64 v[194:195], s[20:21], 0, v[144:145]
	s_mov_b32 m0, s37
	s_nop 0
	global_load_lds_dwordx4 v[194:195], off
	s_waitcnt lgkmcnt(8)
	s_barrier
	s_waitcnt lgkmcnt(0)
	s_setprio 1
	s_waitcnt lgkmcnt(0)
	v_mfma_f32_16x16x32_bf16 v[140:143], v[96:99], v[156:159], v[140:143]
	v_mfma_f32_16x16x32_bf16 v[136:139], v[120:123], v[156:159], v[136:139]
	v_mfma_f32_16x16x32_bf16 v[128:131], v[96:99], v[170:173], v[128:131]
	v_mfma_f32_16x16x32_bf16 v[124:127], v[120:123], v[170:173], v[124:127]
	v_mfma_f32_16x16x32_bf16 v[112:115], v[96:99], v[178:181], v[112:115]
	v_mfma_f32_16x16x32_bf16 v[100:103], v[120:123], v[178:181], v[100:103]
	v_mfma_f32_16x16x32_bf16 v[88:91], v[96:99], v[186:189], v[88:91]
	v_mfma_f32_16x16x32_bf16 v[80:83], v[120:123], v[186:189], v[80:83]
	v_mfma_f32_16x16x32_bf16 v[140:143], v[108:111], v[166:169], v[140:143]
	v_mfma_f32_16x16x32_bf16 v[136:139], v[132:135], v[166:169], v[136:139]
	v_mfma_f32_16x16x32_bf16 v[128:131], v[108:111], v[174:177], v[128:131]
	v_mfma_f32_16x16x32_bf16 v[124:127], v[132:135], v[174:177], v[124:127]
	v_mfma_f32_16x16x32_bf16 v[112:115], v[108:111], v[182:185], v[112:115]
	v_mfma_f32_16x16x32_bf16 v[100:103], v[132:135], v[182:185], v[100:103]
	v_mfma_f32_16x16x32_bf16 v[88:91], v[108:111], v[190:193], v[88:91]
	v_mfma_f32_16x16x32_bf16 v[80:83], v[132:135], v[190:193], v[80:83]
	s_setprio 0
	s_barrier
	s_add_i32 s26, 0, 0x1c000
	s_add_i32 s20, s55, s30
	v_add_u32_e32 v206, s26, v162
	v_lshl_add_u64 v[160:161], v[160:161], 0, s[12:13]
	s_mov_b32 m0, s20
	ds_read_b128 v[194:197], v206
	ds_read_b128 v[198:201], v206 offset:1024
	ds_read_b128 v[202:205], v206 offset:2048
	ds_read_b128 v[206:209], v206 offset:3072
	global_load_lds_dwordx4 v[160:161], off
	v_lshl_add_u64 v[160:161], v[210:211], 0, s[12:13]
	s_add_i32 m0, s20, 0x2000
	s_nop 0
	global_load_lds_dwordx4 v[160:161], off
	s_barrier
	s_waitcnt lgkmcnt(0)
	s_setprio 1
	s_waitcnt lgkmcnt(0)
	v_mfma_f32_16x16x32_bf16 v[116:119], v[194:197], v[156:159], v[116:119]
	v_mfma_f32_16x16x32_bf16 v[104:107], v[202:205], v[156:159], v[104:107]
	v_mfma_f32_16x16x32_bf16 v[92:95], v[194:197], v[170:173], v[92:95]
	v_mfma_f32_16x16x32_bf16 v[84:87], v[202:205], v[170:173], v[84:87]
	v_mfma_f32_16x16x32_bf16 v[76:79], v[194:197], v[178:181], v[76:79]
	v_mfma_f32_16x16x32_bf16 v[72:75], v[202:205], v[178:181], v[72:75]
	v_mfma_f32_16x16x32_bf16 v[68:71], v[194:197], v[186:189], v[68:71]
	v_mfma_f32_16x16x32_bf16 v[64:67], v[202:205], v[186:189], v[64:67]
	v_mfma_f32_16x16x32_bf16 v[116:119], v[198:201], v[166:169], v[116:119]
	v_mfma_f32_16x16x32_bf16 v[104:107], v[206:209], v[166:169], v[104:107]
	v_mfma_f32_16x16x32_bf16 v[92:95], v[198:201], v[174:177], v[92:95]
	v_mfma_f32_16x16x32_bf16 v[84:87], v[206:209], v[174:177], v[84:87]
	v_mfma_f32_16x16x32_bf16 v[76:79], v[198:201], v[182:185], v[76:79]
	v_mfma_f32_16x16x32_bf16 v[72:75], v[206:209], v[182:185], v[72:75]
	v_mfma_f32_16x16x32_bf16 v[68:71], v[198:201], v[190:193], v[68:71]
	v_mfma_f32_16x16x32_bf16 v[64:67], v[206:209], v[190:193], v[64:67]
	s_setprio 0
	s_mov_b32 m0, s44
	v_lshl_add_u64 v[160:161], v[212:213], 0, s[12:13]
	s_barrier
	ds_read_b128 v[156:159], v164 offset:49152
	ds_read_b128 v[166:169], v164 offset:50176
	ds_read_b128 v[170:173], v164 offset:51200
	ds_read_b128 v[174:177], v164 offset:52224
	ds_read_b128 v[178:181], v164 offset:53248
	ds_read_b128 v[182:185], v164 offset:54272
	ds_read_b128 v[186:189], v164 offset:55296
	ds_read_b128 v[190:193], v164 offset:56320
	global_load_lds_dwordx4 v[160:161], off
	v_lshl_add_u64 v[160:161], v[214:215], 0, s[12:13]
	s_mov_b32 m0, s45
	s_nop 0
	global_load_lds_dwordx4 v[160:161], off
	s_barrier
; #define PG8_STAGE(bufoff, gbase, voff) do { _Pragma("unroll") for (int _i = 0; _i < 2; ++_i) \
;         __builtin_amdgcn_global_load_lds((const unsigned*)((const char*)(gbase) + (voff)[_i]), (LAS unsigned*)(lds + (bufoff) + ldsw + _i * 8192), 16, 0, 0); } while (0)
; #define PG8_MMA(ai, bj, At, Bt) do { __builtin_amdgcn_s_setprio(1); _Pragma("unroll") for (int m = 0; m < 4; ++m) _Pragma("unroll") for (int n = 0; n < 2; ++n) _Pragma("unroll") for (int k = 0; k < 2; ++k) \
;         acc[ai][bj][m][n] = __builtin_amdgcn_mfma_f32_16x16x32_bf16(Bt[n][k], At[m][k], acc[ai][bj][m][n], 0, 0, 0); __builtin_amdgcn_s_setprio(0); } while (0)
; #define PG8_WAIT_V(n) asm volatile("s_waitcnt vmcnt(" #n ")" ::: "memory")
; #define PG8_WAIT_L(n) asm volatile("s_waitcnt lgkmcnt(" #n ")" ::: "memory")
; #define PG8_BAR __builtin_amdgcn_s_barrier()
; template <class Epi>
; __device__ __forceinline__ void gemm_phase(LAS unsigned char* lds, const Gemm g, const StaticOrder& S, const Epi& E, int wave) {
;     ...
;             PG8_BAR; PG8_WAIT_L(0); PG8_MMA(1, 0, At, B0); PG8_BAR; PG8_SCHED;
;             PG8_STAGE(PG8_SB(1, 1), b3 + hstep, voffB);
;             PG8_WAIT_V(6); PG8_BAR; PG8_MMA(1, 1, At, B1); PG8_BAR;
;         }
;     __device__ __forceinline__ void operator()(const f32x4 (&acc)[2][2][4][2], const pg8::Unit& u, int wr, int wc, int, int) const {
;         int ln_; asm volatile("v_mbcnt_lo_u32_b32 %0, -1, 0\n\tv_mbcnt_hi_u32_b32 %0, -1, %0" : "=v"(ln_)); const int fr = ln_ & 15, fq = ln_ >> 4;
;         const int row0 = u.pm * 256 + wr * 64 + fr, col0 = u.pn * 256 + wc * 32 + 4 * fq;
;         const int bi = batch_of(u.pm * 256);
;         const float* base = (u.pm * 256 < NPTOK) ? basep : bases - (size_t)NPTOK * D;
;         f32x4 gv[2][2];
; #pragma unroll
;         for (int bj = 0; bj < 2; ++bj)
; #pragma unroll
;             for (int n = 0; n < 2; ++n) gv[bj][n] = *(const f32x4*)(gate + (size_t)bi * MODW + col0 + bj * HALF + n * 16);
; #pragma unroll
;         for (int ai = 0; ai < 2; ++ai) {
;             f32x4 bv[4][2][2];
; #pragma unroll
;             for (int m = 0; m < 4; ++m) { const size_t off = (size_t)(row0 + ai * HALF + m * 16) * D + col0;
; #pragma unroll
;                 for (int bj = 0; bj < 2; ++bj)
; #pragma unroll
;                     for (int n = 0; n < 2; ++n) bv[m][bj][n] = *(const f32x4*)(base + off + bj * HALF + n * 16); }
	s_waitcnt lgkmcnt(0)
	s_setprio 1
	s_waitcnt lgkmcnt(0)
	v_mfma_f32_16x16x32_bf16 v[60:63], v[96:99], v[156:159], v[60:63]
	v_mfma_f32_16x16x32_bf16 v[56:59], v[120:123], v[156:159], v[56:59]
	v_mfma_f32_16x16x32_bf16 v[52:55], v[96:99], v[170:173], v[52:55]
	v_mfma_f32_16x16x32_bf16 v[44:47], v[120:123], v[170:173], v[44:47]
	v_mfma_f32_16x16x32_bf16 v[36:39], v[96:99], v[178:181], v[36:39]
	v_mfma_f32_16x16x32_bf16 v[28:31], v[120:123], v[178:181], v[28:31]
	v_mfma_f32_16x16x32_bf16 v[20:23], v[96:99], v[186:189], v[20:23]
	v_mfma_f32_16x16x32_bf16 v[8:11], v[120:123], v[186:189], v[8:11]
	v_mfma_f32_16x16x32_bf16 v[60:63], v[108:111], v[166:169], v[60:63]
	v_mfma_f32_16x16x32_bf16 v[56:59], v[132:135], v[166:169], v[56:59]
	v_mfma_f32_16x16x32_bf16 v[52:55], v[108:111], v[174:177], v[52:55]
	v_mfma_f32_16x16x32_bf16 v[44:47], v[132:135], v[174:177], v[44:47]
	v_mfma_f32_16x16x32_bf16 v[36:39], v[108:111], v[182:185], v[36:39]
	v_mfma_f32_16x16x32_bf16 v[28:31], v[132:135], v[182:185], v[28:31]
	v_mfma_f32_16x16x32_bf16 v[20:23], v[108:111], v[190:193], v[20:23]
	v_mfma_f32_16x16x32_bf16 v[8:11], v[132:135], v[190:193], v[8:11]
	s_setprio 0
	s_barrier
	s_add_u32 s20, s24, 0xb0080
	s_addc_u32 s21, s25, 0
	s_add_i32 s24, s26, s30
	v_lshl_add_u64 v[96:97], s[20:21], 0, v[146:147]
	s_mov_b32 m0, s24
	s_nop 0
	global_load_lds_dwordx4 v[96:97], off
	v_lshl_add_u64 v[96:97], s[20:21], 0, v[144:145]
	s_add_i32 m0, s24, 0x2000
	s_nop 0
	global_load_lds_dwordx4 v[96:97], off
	s_waitcnt vmcnt(6)
	s_barrier
	s_setprio 1
	v_mfma_f32_16x16x32_bf16 v[48:51], v[194:197], v[156:159], v[48:51]
	v_mfma_f32_16x16x32_bf16 v[40:43], v[202:205], v[156:159], v[40:43]
	v_mfma_f32_16x16x32_bf16 v[32:35], v[194:197], v[170:173], v[32:35]
	v_mfma_f32_16x16x32_bf16 v[24:27], v[202:205], v[170:173], v[24:27]
	v_mfma_f32_16x16x32_bf16 v[16:19], v[194:197], v[178:181], v[16:19]
	v_mfma_f32_16x16x32_bf16 v[12:15], v[202:205], v[178:181], v[12:15]
	v_mfma_f32_16x16x32_bf16 v[4:7], v[194:197], v[186:189], v[4:7]
	v_mfma_f32_16x16x32_bf16 v[0:3], v[202:205], v[186:189], v[0:3]
	v_mfma_f32_16x16x32_bf16 v[48:51], v[198:201], v[166:169], v[48:51]
	v_mfma_f32_16x16x32_bf16 v[40:43], v[206:209], v[166:169], v[40:43]
	v_mfma_f32_16x16x32_bf16 v[32:35], v[198:201], v[174:177], v[32:35]
	v_mfma_f32_16x16x32_bf16 v[24:27], v[206:209], v[174:177], v[24:27]
	v_mfma_f32_16x16x32_bf16 v[16:19], v[198:201], v[182:185], v[16:19]
	v_mfma_f32_16x16x32_bf16 v[12:15], v[206:209], v[182:185], v[12:15]
	v_mfma_f32_16x16x32_bf16 v[4:7], v[198:201], v[190:193], v[4:7]
	v_mfma_f32_16x16x32_bf16 v[0:3], v[206:209], v[190:193], v[0:3]
	s_setprio 0
	s_add_i32 s54, s54, 2
	s_add_u32 s52, s52, 0x100
	s_addc_u32 s53, s53, 0
	s_cmp_gt_u32 s54, 41
	s_mov_b64 s[20:21], s[22:23]
	s_barrier
	s_cbranch_scc0 .LBB0_889
	s_lshl_b32 s20, s50, 8
	v_mbcnt_lo_u32_b32 v158, -1, 0
	v_mbcnt_hi_u32_b32 v158, -1, v158
	s_add_i32 s22, s20, s42
	s_lshl_b32 s21, s51, 8
	v_ashrrev_i32_e32 v96, 2, v158
	s_min_i32 s20, s20, 0x10000
	s_or_b32 s21, s21, s43
	v_and_b32_e32 v96, -4, v96
	s_ashr_i32 s20, s20, 11
	v_add_u32_e32 v96, s21, v96
	s_mul_hi_i32 s21, s20, 0x6000
	s_mulk_i32 s20, 0x6000
	s_add_u32 s20, s39, s20
	v_ashrrev_i32_e32 v97, 31, v96
	s_addc_u32 s21, s40, s21
	v_lshlrev_b64 v[156:157], 2, v[96:97]
	v_lshl_add_u64 v[96:97], s[20:21], 0, v[156:157]
	v_and_or_b32 v214, v158, 15, s22
	v_readlane_b32 s20, v253, 8
	v_readlane_b32 s21, v253, 9
	v_ashrrev_i32_e32 v215, 31, v214
	v_lshlrev_b64 v[160:161], 12, v[214:215]
	v_lshl_add_u64 v[158:159], s[20:21], 0, v[156:157]
	v_or_b32_e32 v182, 16, v214
	v_lshl_add_u64 v[178:179], v[158:159], 0, v[160:161]
	v_ashrrev_i32_e32 v183, 31, v182
	global_load_dwordx4 v[132:135], v[96:97], off
	global_load_dwordx4 v[120:123], v[96:97], off offset:64
	global_load_dwordx4 v[108:111], v[96:97], off offset:512
	s_nop 0
	global_load_dwordx4 v[96:99], v[96:97], off offset:576
	s_nop 0
	global_load_dwordx4 v[166:169], v[178:179], off
	global_load_dwordx4 v[170:173], v[178:179], off offset:64
	global_load_dwordx4 v[174:177], v[178:179], off offset:512
	s_nop 0
	global_load_dwordx4 v[178:181], v[178:179], off offset:576
	v_lshlrev_b64 v[230:231], 12, v[182:183]
	v_or_b32_e32 v198, 32, v214
	v_lshl_add_u64 v[194:195], v[158:159], 0, v[230:231]
	v_ashrrev_i32_e32 v199, 31, v198
	global_load_dwordx4 v[182:185], v[194:195], off
	global_load_dwordx4 v[186:189], v[194:195], off offset:64
	global_load_dwordx4 v[190:193], v[194:195], off offset:512
	s_nop 0
	global_load_dwordx4 v[194:197], v[194:195], off offset:576
	v_lshlrev_b64 v[232:233], 12, v[198:199]
	v_or_b32_e32 v214, 48, v214
	v_lshl_add_u64 v[210:211], v[158:159], 0, v[232:233]
	v_ashrrev_i32_e32 v215, 31, v214
	global_load_dwordx4 v[198:201], v[210:211], off
	global_load_dwordx4 v[202:205], v[210:211], off offset:64
	global_load_dwordx4 v[206:209], v[210:211], off offset:512
	s_nop 0
	global_load_dwordx4 v[210:213], v[210:211], off offset:576
	v_lshlrev_b64 v[234:235], 12, v[214:215]
	v_lshl_add_u64 v[226:227], v[158:159], 0, v[234:235]
	global_load_dwordx4 v[214:217], v[226:227], off
	global_load_dwordx4 v[218:221], v[226:227], off offset:64
	global_load_dwordx4 v[222:225], v[226:227], off offset:512
	s_nop 0
	global_load_dwordx4 v[226:229], v[226:227], off offset:576
	v_readlane_b32 s22, v253, 10
	v_readlane_b32 s23, v253, 11
	s_and_b64 vcc, exec, s[0:1]
	s_mov_b32 s51, s48
	s_mov_b32 s50, s49
	s_mov_b64 s[22:23], s[4:5]
	s_waitcnt vmcnt(12)
;     __device__ __forceinline__ void operator()(const f32x4 (&acc)[2][2][4][2], const pg8::Unit& u, int wr, int wc, int, int) const {
;     ...
;         for (int ai = 0; ai < 2; ++ai) {
;             f32x4 bv[4][2][2];
; #pragma unroll
;             for (int m = 0; m < 4; ++m) { const size_t off = (size_t)(row0 + ai * HALF + m * 16) * D + col0;
; #pragma unroll
;                 for (int bj = 0; bj < 2; ++bj)
; #pragma unroll
;                     for (int n = 0; n < 2; ++n) bv[m][bj][n] = *(const f32x4*)(base + off + bj * HALF + n * 16); }
; #pragma unroll
;             for (int m = 0; m < 4; ++m) { const size_t off = (size_t)(row0 + ai * HALF + m * 16) * D + col0;
; #pragma unroll
;                 for (int bj = 0; bj < 2; ++bj)
; #pragma unroll
;                     for (int n = 0; n < 2; ++n) *(f32x4*)(out + off + bj * HALF + n * 16) = bv[m][bj][n] + gv[bj][n] * acc[ai][bj][m][n]; }
	v_pk_fma_f32 v[142:143], v[142:143], v[134:135], v[168:169]
	v_pk_fma_f32 v[140:141], v[140:141], v[132:133], v[166:167]
	v_pk_fma_f32 v[138:139], v[138:139], v[122:123], v[172:173]
	v_pk_fma_f32 v[136:137], v[136:137], v[120:121], v[170:171]
	v_pk_fma_f32 v[118:119], v[118:119], v[110:111], v[176:177]
	v_pk_fma_f32 v[116:117], v[116:117], v[108:109], v[174:175]
	v_pk_fma_f32 v[106:107], v[106:107], v[98:99], v[180:181]
	v_pk_fma_f32 v[104:105], v[104:105], v[96:97], v[178:179]
	v_lshl_add_u64 v[236:237], v[160:161], 0, s[14:15]
	v_lshl_add_u64 v[236:237], v[158:159], 0, v[236:237]
	global_load_dwordx4 v[166:169], v[236:237], off
	global_load_dwordx4 v[170:173], v[236:237], off offset:64
	global_load_dwordx4 v[174:177], v[236:237], off offset:512
	global_load_dwordx4 v[178:181], v[236:237], off offset:576
	s_waitcnt vmcnt(12)
	v_pk_fma_f32 v[130:131], v[130:131], v[134:135], v[184:185]
	v_pk_fma_f32 v[128:129], v[128:129], v[132:133], v[182:183]
	v_pk_fma_f32 v[126:127], v[126:127], v[122:123], v[188:189]
	v_pk_fma_f32 v[124:125], v[124:125], v[120:121], v[186:187]
	v_pk_fma_f32 v[94:95], v[94:95], v[110:111], v[192:193]
	v_pk_fma_f32 v[92:93], v[92:93], v[108:109], v[190:191]
	v_pk_fma_f32 v[86:87], v[86:87], v[98:99], v[196:197]
	v_pk_fma_f32 v[84:85], v[84:85], v[96:97], v[194:195]
	v_lshl_add_u64 v[238:239], v[160:161], 0, s[16:17]
	v_lshl_add_u64 v[238:239], v[158:159], 0, v[238:239]
	global_load_dwordx4 v[182:185], v[238:239], off
	global_load_dwordx4 v[186:189], v[238:239], off offset:64
	global_load_dwordx4 v[190:193], v[238:239], off offset:512
	global_load_dwordx4 v[194:197], v[238:239], off offset:576
	s_waitcnt vmcnt(12)
	v_pk_fma_f32 v[114:115], v[114:115], v[134:135], v[200:201]
	v_pk_fma_f32 v[112:113], v[112:113], v[132:133], v[198:199]
	v_pk_fma_f32 v[102:103], v[102:103], v[122:123], v[204:205]
	v_pk_fma_f32 v[100:101], v[100:101], v[120:121], v[202:203]
	v_pk_fma_f32 v[78:79], v[78:79], v[110:111], v[208:209]
	v_pk_fma_f32 v[76:77], v[76:77], v[108:109], v[206:207]
	v_pk_fma_f32 v[74:75], v[74:75], v[98:99], v[212:213]
	v_pk_fma_f32 v[72:73], v[72:73], v[96:97], v[210:211]
	v_lshl_add_u64 v[236:237], v[160:161], 0, s[18:19]
	v_lshl_add_u64 v[236:237], v[158:159], 0, v[236:237]
	global_load_dwordx4 v[198:201], v[236:237], off
	global_load_dwordx4 v[202:205], v[236:237], off offset:64
	global_load_dwordx4 v[206:209], v[236:237], off offset:512
	global_load_dwordx4 v[210:213], v[236:237], off offset:576
	s_waitcnt vmcnt(12)
	v_pk_fma_f32 v[90:91], v[90:91], v[134:135], v[216:217]
	v_pk_fma_f32 v[88:89], v[88:89], v[132:133], v[214:215]
	v_pk_fma_f32 v[82:83], v[82:83], v[122:123], v[220:221]
	v_pk_fma_f32 v[80:81], v[80:81], v[120:121], v[218:219]
	v_pk_fma_f32 v[70:71], v[70:71], v[110:111], v[224:225]
	v_pk_fma_f32 v[68:69], v[68:69], v[108:109], v[222:223]
	v_pk_fma_f32 v[66:67], v[66:67], v[98:99], v[228:229]
	v_pk_fma_f32 v[64:65], v[64:65], v[96:97], v[226:227]
	v_lshl_add_u64 v[238:239], v[160:161], 0, s[10:11]
	v_lshl_add_u64 v[238:239], v[158:159], 0, v[238:239]
	global_load_dwordx4 v[214:217], v[238:239], off
	global_load_dwordx4 v[218:221], v[238:239], off offset:64
	global_load_dwordx4 v[222:225], v[238:239], off offset:512
	global_load_dwordx4 v[226:229], v[238:239], off offset:576
	v_lshl_add_u64 v[240:241], s[20:21], 0, v[160:161]
	v_lshl_add_u64 v[240:241], v[240:241], 0, v[156:157]
	global_store_dwordx4 v[240:241], v[140:143], off
	global_store_dwordx4 v[240:241], v[136:139], off offset:64
	global_store_dwordx4 v[240:241], v[116:119], off offset:512
	global_store_dwordx4 v[240:241], v[104:107], off offset:576
	v_lshl_add_u64 v[242:243], s[20:21], 0, v[230:231]
	v_lshl_add_u64 v[242:243], v[242:243], 0, v[156:157]
	global_store_dwordx4 v[242:243], v[128:131], off
	global_store_dwordx4 v[242:243], v[124:127], off offset:64
	global_store_dwordx4 v[242:243], v[92:95], off offset:512
	global_store_dwordx4 v[242:243], v[84:87], off offset:576
	v_lshl_add_u64 v[240:241], s[20:21], 0, v[232:233]
	v_lshl_add_u64 v[240:241], v[240:241], 0, v[156:157]
	global_store_dwordx4 v[240:241], v[112:115], off
	global_store_dwordx4 v[240:241], v[100:103], off offset:64
	global_store_dwordx4 v[240:241], v[76:79], off offset:512
	global_store_dwordx4 v[240:241], v[72:75], off offset:576
	v_lshl_add_u64 v[242:243], s[20:21], 0, v[234:235]
	v_lshl_add_u64 v[242:243], v[242:243], 0, v[156:157]
	global_store_dwordx4 v[242:243], v[88:91], off
	global_store_dwordx4 v[242:243], v[80:83], off offset:64
	global_store_dwordx4 v[242:243], v[68:71], off offset:512
	global_store_dwordx4 v[242:243], v[64:67], off offset:576
	v_lshl_add_u64 v[244:245], v[160:161], 0, s[14:15]
	v_lshl_add_u64 v[244:245], s[20:21], 0, v[244:245]
	v_lshl_add_u64 v[244:245], v[244:245], 0, v[156:157]
	s_waitcnt vmcnt(28)
;     __device__ __forceinline__ void operator()(const f32x4 (&acc)[2][2][4][2], const pg8::Unit& u, int wr, int wc, int, int) const {
;     ...
;         for (int ai = 0; ai < 2; ++ai) {
;             f32x4 bv[4][2][2];
; #pragma unroll
;             for (int m = 0; m < 4; ++m) { const size_t off = (size_t)(row0 + ai * HALF + m * 16) * D + col0;
; #pragma unroll
;                 for (int bj = 0; bj < 2; ++bj)
; #pragma unroll
;                     for (int n = 0; n < 2; ++n) bv[m][bj][n] = *(const f32x4*)(base + off + bj * HALF + n * 16); }
; #pragma unroll
;             for (int m = 0; m < 4; ++m) { const size_t off = (size_t)(row0 + ai * HALF + m * 16) * D + col0;
; #pragma unroll
;                 for (int bj = 0; bj < 2; ++bj)
; #pragma unroll
;                     for (int n = 0; n < 2; ++n) *(f32x4*)(out + off + bj * HALF + n * 16) = bv[m][bj][n] + gv[bj][n] * acc[ai][bj][m][n]; }
	v_pk_fma_f32 v[62:63], v[62:63], v[134:135], v[168:169]
	v_pk_fma_f32 v[60:61], v[60:61], v[132:133], v[166:167]
	v_pk_fma_f32 v[58:59], v[58:59], v[122:123], v[172:173]
	v_pk_fma_f32 v[56:57], v[56:57], v[120:121], v[170:171]
	v_pk_fma_f32 v[50:51], v[50:51], v[110:111], v[176:177]
	v_pk_fma_f32 v[48:49], v[48:49], v[108:109], v[174:175]
	v_pk_fma_f32 v[42:43], v[42:43], v[98:99], v[180:181]
	v_pk_fma_f32 v[40:41], v[40:41], v[96:97], v[178:179]
	global_store_dwordx4 v[244:245], v[60:63], off
	global_store_dwordx4 v[244:245], v[56:59], off offset:64
	global_store_dwordx4 v[244:245], v[48:51], off offset:512
	global_store_dwordx4 v[244:245], v[40:43], off offset:576
	v_lshl_add_u64 v[246:247], v[160:161], 0, s[16:17]
	v_lshl_add_u64 v[246:247], s[20:21], 0, v[246:247]
	v_lshl_add_u64 v[246:247], v[246:247], 0, v[156:157]
	s_waitcnt vmcnt(28)
	v_pk_fma_f32 v[54:55], v[54:55], v[134:135], v[184:185]
	v_pk_fma_f32 v[52:53], v[52:53], v[132:133], v[182:183]
	v_pk_fma_f32 v[46:47], v[46:47], v[122:123], v[188:189]
	v_pk_fma_f32 v[44:45], v[44:45], v[120:121], v[186:187]
	v_pk_fma_f32 v[34:35], v[34:35], v[110:111], v[192:193]
	v_pk_fma_f32 v[32:33], v[32:33], v[108:109], v[190:191]
	v_pk_fma_f32 v[26:27], v[26:27], v[98:99], v[196:197]
	v_pk_fma_f32 v[24:25], v[24:25], v[96:97], v[194:195]
	global_store_dwordx4 v[246:247], v[52:55], off
	global_store_dwordx4 v[246:247], v[44:47], off offset:64
	global_store_dwordx4 v[246:247], v[32:35], off offset:512
	global_store_dwordx4 v[246:247], v[24:27], off offset:576
	v_lshl_add_u64 v[244:245], v[160:161], 0, s[18:19]
	v_lshl_add_u64 v[244:245], s[20:21], 0, v[244:245]
	v_lshl_add_u64 v[244:245], v[244:245], 0, v[156:157]
	s_waitcnt vmcnt(28)
	v_pk_fma_f32 v[38:39], v[38:39], v[134:135], v[200:201]
	v_pk_fma_f32 v[36:37], v[36:37], v[132:133], v[198:199]
	v_pk_fma_f32 v[30:31], v[30:31], v[122:123], v[204:205]
	v_pk_fma_f32 v[28:29], v[28:29], v[120:121], v[202:203]
	v_pk_fma_f32 v[18:19], v[18:19], v[110:111], v[208:209]
	v_pk_fma_f32 v[16:17], v[16:17], v[108:109], v[206:207]
	v_pk_fma_f32 v[14:15], v[14:15], v[98:99], v[212:213]
	v_pk_fma_f32 v[12:13], v[12:13], v[96:97], v[210:211]
	global_store_dwordx4 v[244:245], v[36:39], off
	global_store_dwordx4 v[244:245], v[28:31], off offset:64
	global_store_dwordx4 v[244:245], v[16:19], off offset:512
	global_store_dwordx4 v[244:245], v[12:15], off offset:576
	v_lshl_add_u64 v[246:247], v[160:161], 0, s[10:11]
	v_lshl_add_u64 v[246:247], s[20:21], 0, v[246:247]
	v_lshl_add_u64 v[246:247], v[246:247], 0, v[156:157]
	s_waitcnt vmcnt(28)
	v_pk_fma_f32 v[22:23], v[22:23], v[134:135], v[216:217]
	v_pk_fma_f32 v[20:21], v[20:21], v[132:133], v[214:215]
	v_pk_fma_f32 v[10:11], v[10:11], v[122:123], v[220:221]
	v_pk_fma_f32 v[8:9], v[8:9], v[120:121], v[218:219]
	v_pk_fma_f32 v[6:7], v[6:7], v[110:111], v[224:225]
	v_pk_fma_f32 v[4:5], v[4:5], v[108:109], v[222:223]
	v_pk_fma_f32 v[2:3], v[2:3], v[98:99], v[228:229]
	v_pk_fma_f32 v[0:1], v[0:1], v[96:97], v[226:227]
	s_mov_b64 s[20:21], s[6:7]
	global_store_dwordx4 v[246:247], v[20:23], off
	global_store_dwordx4 v[246:247], v[8:11], off offset:64
	global_store_dwordx4 v[246:247], v[4:7], off offset:512
	global_store_dwordx4 v[246:247], v[0:3], off offset:576
	s_cbranch_vccz .LBB0_882
	s_waitcnt vmcnt(0)
	s_cmpk_gt_u32 s3, 0xff
	s_cbranch_scc1 .LBB0_893
	s_barrier
